# attention-layer in-projection of the 512 sample rows as 640 small 32x64 tiles (K split over 8 waves) instead of 20 full units in an eleventh round
# baseline (speedup 1.0000x reference)
.LBB0_721:
	s_mov_b32 s100, 0
	v_readlane_b32 s2, v252, 26
	v_readlane_b32 s3, v252, 27
	s_and_b64 s[2:3], s[2:3], exec
	s_cbranch_scc1 .Lsi_done
	s_load_dwordx2 s[4:5], s[0:1], 0x98
	s_load_dwordx2 s[6:7], s[0:1], 0x90
	s_and_b32 s11, s61, 0xff
	s_lshr_b32 s12, s11, 1
	v_lshrrev_b32_e32 v1, 6, v210
	v_and_b32_e32 v2, 63, v210
	v_and_b32_e32 v3, 31, v2
	v_lshrrev_b32_e32 v2, 5, v2
	v_lshlrev_b32_e32 v4, 11, v3
	v_lshl_add_u32 v4, v1, 8, v4
	v_lshl_add_u32 v4, v2, 4, v4
	v_add_u32_e32 v5, 0x10000, v4
	v_lshlrev_b32_e32 v6, 5, v1
	v_lshl_add_u32 v6, v2, 2, v6
	v_lshlrev_b32_e32 v6, 8, v6
	v_lshl_add_u32 v6, v3, 2, v6
	v_lshrrev_b32_e32 v8, 4, v210
	v_and_b32_e32 v9, 15, v210
	v_lshlrev_b32_e32 v9, 2, v9
	v_lshlrev_b32_e32 v7, 8, v8
	v_lshl_add_u32 v7, v9, 2, v7
	s_mov_b32 s8, s80
	s_waitcnt lgkmcnt(0)
	s_mul_i32 s13, s12, 0x500000
	s_add_u32 s20, s4, 0x1e00000
	s_addc_u32 s21, s5, 0
	s_add_u32 s20, s20, s13
	s_addc_u32 s21, s21, 0
	s_mul_i32 s13, s11, 0x102000
	s_add_u32 s22, s4, 0x27600000
	s_addc_u32 s23, s5, 0
	s_add_u32 s22, s22, s13
	s_addc_u32 s23, s23, 0
	s_mul_i32 s13, s11, 0x90000
	s_add_u32 s26, s4, 0x500000
	s_addc_u32 s27, s5, 0
	s_add_u32 s26, s26, s13
	s_addc_u32 s27, s27, 0
	s_lshl_b32 s13, s12, 21
	s_add_u32 s6, s6, s13
	s_addc_u32 s7, s7, 0
	s_cmp_lt_u32 s8, 0x280
	s_cbranch_scc0 .Lsi_done
.Lsi_tile:
	s_mul_i32 s9, s8, 0x667
	s_lshr_b32 s9, s9, 16
	s_mul_i32 s10, s9, 40
	s_sub_u32 s10, s8, s10
	s_lshl_b32 s13, s9, 16
	s_add_u32 s14, s4, 0x3000000
	s_addc_u32 s15, s5, 0
	s_add_u32 s14, s14, 0x8000000
	s_addc_u32 s15, s15, 0
	s_add_u32 s14, s14, s13
	s_addc_u32 s15, s15, 0
	s_lshl_b32 s13, s10, 17
	s_add_u32 s16, s20, s13
	s_addc_u32 s17, s21, 0
	global_load_dwordx4 v[16:19], v4, s[14:15]
	global_load_dwordx4 v[20:23], v4, s[14:15] offset:32
	global_load_dwordx4 v[24:27], v4, s[14:15] offset:64
	global_load_dwordx4 v[28:31], v4, s[14:15] offset:96
	global_load_dwordx4 v[32:35], v4, s[14:15] offset:128
	global_load_dwordx4 v[36:39], v4, s[14:15] offset:160
	global_load_dwordx4 v[40:43], v4, s[14:15] offset:192
	global_load_dwordx4 v[44:47], v4, s[14:15] offset:224
	global_load_dwordx4 v[48:51], v4, s[16:17]
	global_load_dwordx4 v[52:55], v4, s[16:17] offset:32
	global_load_dwordx4 v[56:59], v4, s[16:17] offset:64
	global_load_dwordx4 v[60:63], v4, s[16:17] offset:96
	global_load_dwordx4 v[64:67], v4, s[16:17] offset:128
	global_load_dwordx4 v[68:71], v4, s[16:17] offset:160
	global_load_dwordx4 v[72:75], v4, s[16:17] offset:192
	global_load_dwordx4 v[76:79], v4, s[16:17] offset:224
	global_load_dwordx4 v[98:101], v5, s[16:17]
	global_load_dwordx4 v[102:105], v5, s[16:17] offset:32
	global_load_dwordx4 v[106:109], v5, s[16:17] offset:64
	global_load_dwordx4 v[110:113], v5, s[16:17] offset:96
	global_load_dwordx4 v[114:117], v5, s[16:17] offset:128
	global_load_dwordx4 v[118:121], v5, s[16:17] offset:160
	global_load_dwordx4 v[122:125], v5, s[16:17] offset:192
	global_load_dwordx4 v[126:129], v5, s[16:17] offset:224
	s_lshl_b32 s13, s9, 5
	s_add_i32 s13, s13, 0x10000
	v_add_u32_e32 v10, s13, v8
	v_lshlrev_b32_e32 v11, 4, v10
	global_load_dwordx4 v[162:165], v11, s[22:23]
	s_add_i32 s18, s9, 32
	s_mul_i32 s18, s18, 0x3000
	s_lshl_b32 s19, s10, 8
	s_add_i32 s18, s18, s19
	v_lshl_add_u32 v11, v9, 2, s18
	global_load_dwordx4 v[166:169], v11, s[26:27]
	s_waitcnt vmcnt(17)
	v_mfma_f32_32x32x16_bf16 v[130:145], v[16:19], v[48:51], 0
	s_waitcnt vmcnt(9)
	v_mfma_f32_32x32x16_bf16 v[146:161], v[16:19], v[98:101], 0
	s_waitcnt vmcnt(16)
	v_mfma_f32_32x32x16_bf16 v[130:145], v[20:23], v[52:55], v[130:145]
	s_waitcnt vmcnt(8)
	v_mfma_f32_32x32x16_bf16 v[146:161], v[20:23], v[102:105], v[146:161]
	s_waitcnt vmcnt(15)
	v_mfma_f32_32x32x16_bf16 v[130:145], v[24:27], v[56:59], v[130:145]
	s_waitcnt vmcnt(7)
	v_mfma_f32_32x32x16_bf16 v[146:161], v[24:27], v[106:109], v[146:161]
	s_waitcnt vmcnt(14)
	v_mfma_f32_32x32x16_bf16 v[130:145], v[28:31], v[60:63], v[130:145]
	s_waitcnt vmcnt(6)
	v_mfma_f32_32x32x16_bf16 v[146:161], v[28:31], v[110:113], v[146:161]
	s_waitcnt vmcnt(13)
	v_mfma_f32_32x32x16_bf16 v[130:145], v[32:35], v[64:67], v[130:145]
	s_waitcnt vmcnt(5)
	v_mfma_f32_32x32x16_bf16 v[146:161], v[32:35], v[114:117], v[146:161]
	s_waitcnt vmcnt(12)
	v_mfma_f32_32x32x16_bf16 v[130:145], v[36:39], v[68:71], v[130:145]
	s_waitcnt vmcnt(4)
	v_mfma_f32_32x32x16_bf16 v[146:161], v[36:39], v[118:121], v[146:161]
	s_waitcnt vmcnt(11)
	v_mfma_f32_32x32x16_bf16 v[130:145], v[40:43], v[72:75], v[130:145]
	s_waitcnt vmcnt(3)
	v_mfma_f32_32x32x16_bf16 v[146:161], v[40:43], v[122:125], v[146:161]
	s_waitcnt vmcnt(10)
	v_mfma_f32_32x32x16_bf16 v[130:145], v[44:47], v[76:79], v[130:145]
	s_waitcnt vmcnt(2)
	v_mfma_f32_32x32x16_bf16 v[146:161], v[44:47], v[126:129], v[146:161]
	s_barrier
	s_nop 7
	s_nop 7
	ds_write_b32 v6, v130
	ds_write_b32 v6, v131 offset:256
	ds_write_b32 v6, v132 offset:512
	ds_write_b32 v6, v133 offset:768
	ds_write_b32 v6, v134 offset:2048
	ds_write_b32 v6, v135 offset:2304
	ds_write_b32 v6, v136 offset:2560
	ds_write_b32 v6, v137 offset:2816
	ds_write_b32 v6, v138 offset:4096
	ds_write_b32 v6, v139 offset:4352
	ds_write_b32 v6, v140 offset:4608
	ds_write_b32 v6, v141 offset:4864
	ds_write_b32 v6, v142 offset:6144
	ds_write_b32 v6, v143 offset:6400
	ds_write_b32 v6, v144 offset:6656
	ds_write_b32 v6, v145 offset:6912
	ds_write_b32 v6, v146 offset:128
	ds_write_b32 v6, v147 offset:384
	ds_write_b32 v6, v148 offset:640
	ds_write_b32 v6, v149 offset:896
	ds_write_b32 v6, v150 offset:2176
	ds_write_b32 v6, v151 offset:2432
	ds_write_b32 v6, v152 offset:2688
	ds_write_b32 v6, v153 offset:2944
	ds_write_b32 v6, v154 offset:4224
	ds_write_b32 v6, v155 offset:4480
	ds_write_b32 v6, v156 offset:4736
	ds_write_b32 v6, v157 offset:4992
	ds_write_b32 v6, v158 offset:6272
	ds_write_b32 v6, v159 offset:6528
	ds_write_b32 v6, v160 offset:6784
	ds_write_b32 v6, v161 offset:7040
	s_waitcnt lgkmcnt(0)
	s_barrier
	ds_read_b128 v[16:19], v7
	ds_read_b128 v[20:23], v7 offset:8192
	ds_read_b128 v[24:27], v7 offset:16384
	ds_read_b128 v[28:31], v7 offset:24576
	ds_read_b128 v[32:35], v7 offset:32768
	ds_read_b128 v[36:39], v7 offset:40960
	ds_read_b128 v[40:43], v7 offset:49152
	ds_read_b128 v[44:47], v7 offset:57344
	s_waitcnt lgkmcnt(6)
	v_add_f32_e32 v16, v16, v20
	v_add_f32_e32 v17, v17, v21
	v_add_f32_e32 v18, v18, v22
	v_add_f32_e32 v19, v19, v23
	s_waitcnt lgkmcnt(5)
	v_add_f32_e32 v16, v16, v24
	v_add_f32_e32 v17, v17, v25
	v_add_f32_e32 v18, v18, v26
	v_add_f32_e32 v19, v19, v27
	s_waitcnt lgkmcnt(4)
	v_add_f32_e32 v16, v16, v28
	v_add_f32_e32 v17, v17, v29
	v_add_f32_e32 v18, v18, v30
	v_add_f32_e32 v19, v19, v31
	s_waitcnt lgkmcnt(3)
	v_add_f32_e32 v16, v16, v32
	v_add_f32_e32 v17, v17, v33
	v_add_f32_e32 v18, v18, v34
	v_add_f32_e32 v19, v19, v35
	s_waitcnt lgkmcnt(2)
	v_add_f32_e32 v16, v16, v36
	v_add_f32_e32 v17, v17, v37
	v_add_f32_e32 v18, v18, v38
	v_add_f32_e32 v19, v19, v39
	s_waitcnt lgkmcnt(1)
	v_add_f32_e32 v16, v16, v40
	v_add_f32_e32 v17, v17, v41
	v_add_f32_e32 v18, v18, v42
	v_add_f32_e32 v19, v19, v43
	s_waitcnt lgkmcnt(0)
	v_add_f32_e32 v16, v16, v44
	v_add_f32_e32 v17, v17, v45
	v_add_f32_e32 v18, v18, v46
	v_add_f32_e32 v19, v19, v47
	s_waitcnt vmcnt(0)
	v_add_f32_e32 v12, v162, v163
	v_add_f32_e32 v13, v164, v165
	v_add_f32_e32 v12, v12, v13
	v_fmamk_f32 v12, v12, 0x3a800000, v212
	v_rsq_f32_e32 v12, v12
	s_nop 1
	v_fma_f32 v16, v16, v12, v166
	v_fma_f32 v17, v17, v12, v167
	v_fma_f32 v18, v18, v12, v168
	v_fma_f32 v19, v19, v12, v169
	s_lshl_b32 s19, s10, 6
	v_add_u32_e32 v13, s19, v9
	s_cmp_lt_u32 s10, 16
	s_cbranch_scc1 .Lsi_q
	s_cmp_lt_u32 s10, 24
	s_cbranch_scc1 .Lsi_kv
	v_mul_f32_e32 v20, 0xbfb8aa3b, v16
	v_mul_f32_e32 v21, 0xbfb8aa3b, v17
	v_mul_f32_e32 v22, 0xbfb8aa3b, v18
	v_mul_f32_e32 v23, 0xbfb8aa3b, v19
	v_exp_f32_e32 v20, v20
	v_exp_f32_e32 v21, v21
	v_exp_f32_e32 v22, v22
	v_exp_f32_e32 v23, v23
	v_add_f32_e32 v20, 1.0, v20
	v_add_f32_e32 v21, 1.0, v21
	v_add_f32_e32 v22, 1.0, v22
	v_add_f32_e32 v23, 1.0, v23
	v_rcp_f32_e32 v20, v20
	v_rcp_f32_e32 v21, v21
	v_rcp_f32_e32 v22, v22
	v_rcp_f32_e32 v23, v23
	s_nop 0
	v_pk_mul_f32 v[16:17], v[16:17], v[20:21]
	v_pk_mul_f32 v[18:19], v[18:19], v[22:23]
	v_cvt_pk_bf16_f32 v20, v16, v17
	v_cvt_pk_bf16_f32 v21, v18, v19
	v_lshlrev_b32_e32 v14, 11, v10
	v_lshl_add_u32 v14, v13, 1, v14
	v_subrev_u32_e32 v14, 0xc00, v14
	s_add_u32 s18, s4, 0x13200000
	s_addc_u32 s19, s5, 0
	global_store_dwordx2 v14, v[20:21], s[18:19]
	s_branch .Lsi_next
.Lsi_q:
	s_mov_b32 s18, 0x3e38aa3b
	v_mul_f32_e32 v16, s18, v16
	v_mul_f32_e32 v17, s18, v17
	v_mul_f32_e32 v18, s18, v18
	v_mul_f32_e32 v19, s18, v19
	v_cvt_pk_bf16_f32 v20, v16, v17
	v_cvt_pk_bf16_f32 v21, v18, v19
	v_lshlrev_b32_e32 v14, 11, v10
	v_lshl_add_u32 v14, v13, 1, v14
	s_add_u32 s18, s4, 0xb100000
	s_addc_u32 s19, s5, 0
	global_store_dwordx2 v14, v[20:21], s[18:19]
	s_branch .Lsi_next
.Lsi_kv:
	s_cmp_lt_u32 s10, 20
	s_mov_b32 s18, 0x23400000
	s_mov_b32 s29, 0x25500000
	s_cselect_b32 s18, s18, s29
	s_mov_b32 s19, 0x117a0000
	s_mov_b32 s29, 0x11ba0000
	s_cselect_b32 s19, s19, s29
	s_movk_i32 s28, 0x400
	s_cselect_b32 s28, s28, 0x500
	s_add_u32 s30, s4, s18
	s_addc_u32 s31, s5, 0
	s_add_u32 s18, s6, s19
	s_addc_u32 s19, s7, 0
	v_cvt_pk_bf16_f32 v20, v16, v17
	v_cvt_pk_bf16_f32 v21, v18, v19
	v_subrev_u32_e32 v13, s28, v13
	v_lshlrev_b32_e32 v14, 9, v10
	v_lshl_add_u32 v14, v13, 1, v14
	global_store_dwordx2 v14, v[20:21], s[30:31]
	s_lshl_b32 s28, s9, 7
	s_add_i32 s28, s28, 96
	v_add_u32_e32 v15, s28, v8
	v_lshlrev_b32_e32 v15, 10, v15
	v_lshl_add_u32 v15, v13, 2, v15
	global_store_dwordx4 v15, v[16:19], s[18:19]
.Lsi_next:
	s_add_i32 s8, s8, s25
	s_cmp_lt_u32 s8, 0x280
	s_cbranch_scc1 .Lsi_tile
	s_barrier
.Lsi_done:
	v_readlane_b32 s2, v252, 26
	v_readlane_b32 s3, v252, 27
	s_and_b64 s[2:3], s[2:3], exec
	s_cselect_b32 s10, 8, 10
	s_cselect_b32 s2, 0x88, 0
	s_movk_i32 s28, 0x102
	s_cselect_b32 s28, s28, 0x100
	s_mul_i32 s28, s10, s28
	s_add_i32 s30, s28, s2
	s_cmp_lt_i32 s80, s30
	s_waitcnt vmcnt(0)
	v_mov_b32 v0, v210
	s_cselect_b64 s[4:5], -1, 0
	s_cmp_ge_i32 s80, s30
	v_readfirstlane_b32 s11, v0
	s_cbranch_scc1 .LBB0_730
	s_ashr_i32 s81, s80, 31
	s_not_b64 s[2:3], s[80:81]
	s_add_u32 s6, s30, s2
	s_addc_u32 s7, 0, s3
	s_and_b64 s[2:3], s[82:83], exec
	s_cselect_b32 s7, s7, s81
	s_cselect_b32 s6, s6, s80
	v_mov_b32_e32 v96, s28
	v_cmp_lt_i64_e32 vcc, s[6:7], v[96:97]
	s_mov_b64 s[8:9], -1
	s_cbranch_vccnz .LBB0_724
	s_sub_i32 s2, s6, s28
	s_ashr_i32 s3, s2, 2
	s_and_b32 s2, s6, 3
	s_lshl_b32 s7, s3, 3
	s_or_b32 s2, s2, 8
	s_or_b32 s7, s7, 7
	s_add_i32 s8, s3, 0xe0
	s_cmp_lt_i32 s3, 32
	s_cselect_b32 s36, s7, s8
	s_mov_b64 s[8:9], 0
